# post-projection phase: next-row loads really overlap the current row (body waits only served the first iteration; one wait before the loop and one before the register hand-over)
# speedup vs baseline: 1.0031x; 1.0031x over previous
; __device__ __forceinline__ void post_load(PostRegs& R, int m, int lane, const bf16_t* __restrict__ P, const float* __restrict__ tab32, const float* __restrict__ tab64,
;                                           const float* __restrict__ posK, const float* __restrict__ posV) {
;     const bf16_t* pr = P + (size_t)m * NPJ;
;     const int t = m & (SEQ - 1);
;     const int i16 = 2 * (lane & 7), i32 = 2 * (lane & 15);
;     R.r_cq = *(const u32x2*)(pr + C_CQ + 4 * lane);
;     R.r_ckv = *(const unsigned*)(pr + C_CKV + 2 * lane);
;     R.r_kr1 = *(const unsigned*)(pr + C_KR + i16); R.r_kr2 = *(const unsigned*)(pr + C_KR + 16 + i16);
;     { const int ch = lane >> 3;
;       R.dq1 = *(const unsigned*)(pr + C_DQ + ch * 32 + i16); R.dq2 = *(const unsigned*)(pr + C_DQ + ch * 32 + 16 + i16);
;       R.dk1 = *(const unsigned*)(pr + C_DK + ch * 32 + i16); R.dk2 = *(const unsigned*)(pr + C_DK + ch * 32 + 16 + i16); }
; #pragma unroll
;     for (int rep = 0; rep < 2; ++rep) { const int ch = (lane + 64 * rep) >> 4; R.nq1[rep] = *(const unsigned*)(pr + C_NQ + ch * 64 + i32); R.nq2[rep] = *(const unsigned*)(pr + C_NQ + ch * 64 + 32 + i32); }
; #pragma unroll
;     for (int rep = 0; rep < 2; ++rep) { int ch = (lane + 64 * rep) >> 4; ch = ch < 6 ? ch : 5; const int br = ch >> 1, g = ch & 1;
;         R.nk1[rep] = *(const unsigned*)(pr + C_NKV + br * 256 + g * 64 + i32); R.nk2[rep] = *(const unsigned*)(pr + C_NKV + br * 256 + g * 64 + 32 + i32); }
;     const int vg = (2 * lane) >> 6, vd = (2 * lane) & 63;
;     R.r_v = *(const unsigned*)(pr + C_NKV + 128 + vg * 64 + vd);
;     R.r_gate = pr[C_NG + (lane < 24 ? lane : 23)];
;     R.cs32 = *(const f32x4*)(tab32 + (size_t)t * 32 + 2 * i16);
;     R.cs64 = *(const f32x4*)(tab64 + (size_t)t * 64 + 2 * i32);
;     const int l0 = t & 15, l1 = l0 + 16;
;     R.pk0a = *(const f32x2*)(posK + l0 * 64 + i32); R.pk0b = *(const f32x2*)(posK + l0 * 64 + 32 + i32);
; __device__ __forceinline__ void post_phase(bf16_t* __restrict__ P, const float* __restrict__ tab32, const float* __restrict__ tab64, ...
;     const f32x4 g4 = ((const f32x4*)gq)[lane];
;     const f32x2 g2 = ((const f32x2*)gkv)[lane];
;     const float gb = gate_b[lane < 24 ? lane : 23];
;     if (gw >= MROWS) return;
;     PostRegs Rc, Rn;
;     post_load(Rc, gw, lane, P, tab32, tab64, posK, posV);
.LBB0_933:
	s_andn2_b64 vcc, exec, s[4:5]
	s_cbranch_vccnz .LBB0_960
	global_load_dwordx2 v[6:7], v215, s[8:9] offset:3176
	global_load_dwordx2 v[0:1], v215, s[8:9] offset:3128
	global_load_dwordx2 v[4:5], v215, s[8:9] offset:3208
	global_load_dwordx2 v[2:3], v215, s[8:9] offset:3144
	v_readlane_b32 s26, v254, 43
	s_lshl_b32 s18, s26, 3
	v_readlane_b32 s2, v254, 5
	s_add_i32 s16, s18, s2
	v_readlane_b32 s34, v254, 16
	v_readlane_b32 s36, v254, 20
	v_mov_b32_e32 v9, v246
	s_cmpk_gt_i32 s16, 0x7fff
	v_readlane_b32 s30, v254, 24
	v_readlane_b32 s35, v254, 17
	v_readlane_b32 s37, v254, 21
	s_mov_b32 s38, 0x3e8293ee
	s_mov_b32 s40, 0x3e38aa3b
	v_readlane_b32 s31, v254, 25
	s_waitcnt vmcnt(0)
	v_readfirstlane_b32 s2, v6
	v_readfirstlane_b32 s3, v7
	s_cbranch_scc1 .LBB0_961
	v_readlane_b32 s8, v254, 44
	v_readlane_b32 s9, v254, 45
	s_and_b64 s[4:5], s[8:9], exec
	s_cselect_b32 s4, 0x4000, 0
	s_cselect_b32 s80, 0x60, 0
	s_add_u32 s10, s2, s4
	s_addc_u32 s11, s3, 0
	v_readlane_b32 s6, v254, 50
	v_readlane_b32 s7, v254, 51
	s_add_u32 s12, s6, 0x19ec1000
	s_addc_u32 s13, s7, 0
	v_and_b32_e32 v32, 63, v9
	v_lshl_add_u64 v[4:5], v[4:5], 0, s[80:81]
	s_add_u32 s14, s6, 0x1aec1000
	s_waitcnt lgkmcnt(3)
	v_min_u32_e32 v24, 23, v32
	s_addc_u32 s15, s7, 0
	v_lshlrev_b32_e32 v6, 2, v24
	v_readfirstlane_b32 s2, v4
	v_readfirstlane_b32 s3, v5
	v_readlane_b32 s22, v254, 48
	v_lshlrev_b32_e32 v52, 3, v32
	s_mul_hi_i32 s19, s16, 0x1400
	v_readlane_b32 s23, v254, 49
	v_lshlrev_b32_e32 v16, 1, v32
	global_load_dword v23, v6, s[2:3]
	s_add_u32 s2, s10, 0x2000
	s_addc_u32 s3, s11, 0
	s_and_b64 s[4:5], s[8:9], exec
	s_cselect_b32 s80, 0x200, 0
	v_lshl_add_u64 v[2:3], v[2:3], 0, s[80:81]
	s_cselect_b32 s80, 0x400, 0
	s_add_u32 s4, s6, 0x81000
	v_lshl_add_u64 v[0:1], v[0:1], 0, s[80:81]
	s_addc_u32 s5, s7, 0
	s_add_u32 s6, s6, 0x1000
	v_readfirstlane_b32 s8, v2
	v_lshlrev_b32_e32 v2, 4, v32
	v_readfirstlane_b32 s20, v0
	v_readfirstlane_b32 s21, v1
	s_addc_u32 s7, s7, 0
	v_readfirstlane_b32 s9, v3
	s_ashr_i32 s17, s16, 31
	v_and_b32_e32 v25, 14, v16
	v_and_b32_e32 v10, 0x1c0, v52
	global_load_dwordx4 v[0:3], v2, s[20:21]
	s_mul_i32 s20, s16, 0x1400
	s_add_u32 s22, s22, s20
	s_addc_u32 s23, s23, s19
	v_mov_b32_e32 v11, v215
	v_lshlrev_b32_e32 v4, 1, v25
	v_mov_b32_e32 v5, v215
	v_lshl_add_u64 v[6:7], s[22:23], 0, v[10:11]
	v_and_b32_e32 v8, 30, v16
	global_load_dwordx2 v[20:21], v52, s[8:9]
	global_load_dwordx2 v[92:93], v52, s[22:23]
	global_load_dword v131, v4, s[22:23] offset:768
	global_load_dword v132, v4, s[22:23] offset:800
	v_lshl_add_u64 v[4:5], v[6:7], 0, v[4:5]
	v_and_b32_e32 v6, 0x180, v52
	v_mov_b32_e32 v7, v215
	v_lshl_add_u64 v[6:7], s[22:23], 0, v[6:7]
	v_lshlrev_b32_e32 v12, 1, v8
	v_mov_b32_e32 v13, v215
	v_lshl_add_u64 v[6:7], v[6:7], 0, v[12:13]
	global_load_dword v129, v[4:5], off offset:832
	global_load_dword v130, v[4:5], off offset:864
	global_load_dword v125, v[4:5], off offset:1344
	global_load_dword v126, v[4:5], off offset:1376
	global_load_dword v116, v[6:7], off offset:2368
	global_load_dword v119, v[6:7], off offset:2432
	global_load_dword v109, v[6:7], off offset:2880
	global_load_dword v110, v[6:7], off offset:2944
	v_lshlrev_b32_e32 v4, 4, v9
	v_and_b32_e32 v4, 0x200, v4
	v_mov_b32_e32 v5, v215
	v_lshl_add_u64 v[4:5], s[22:23], 0, v[4:5]
	v_and_b32_e32 v6, 0x80, v52
	v_mov_b32_e32 v7, v215
	v_or_b32_e32 v33, 64, v32
	v_lshl_add_u64 v[4:5], v[4:5], 0, v[6:7]
	v_min_u32_e32 v6, 0x5f, v33
	v_lshlrev_b32_e32 v6, 3, v6
	v_and_b32_e32 v14, 0x80, v6
	v_mov_b32_e32 v15, v215
	v_lshl_add_u64 v[6:7], s[22:23], 0, v[14:15]
	v_lshlrev_b32_e32 v214, 2, v32
	v_lshl_add_u64 v[6:7], v[6:7], 0, v[12:13]
	s_mov_b64 s[8:9], 0x1140
	v_lshl_add_u64 v[4:5], v[4:5], 0, v[12:13]
	v_lshl_add_u64 v[12:13], v[6:7], 0, s[8:9]
	s_movk_i32 s8, 0x1000
	v_and_b32_e32 v22, 62, v16
	v_and_b32_e32 v16, 0x80, v214
	v_mov_b32_e32 v17, v215
	v_add_co_u32_e32 v6, vcc, s8, v6
	v_lshl_add_u64 v[16:17], s[22:23], 0, v[16:17]
	v_lshlrev_b32_e32 v18, 1, v22
	v_mov_b32_e32 v19, v215
	v_lshlrev_b32_e32 v46, 1, v24
	v_mov_b32_e32 v47, v215
	v_addc_co_u32_e32 v7, vcc, 0, v7, vcc
	v_lshl_add_u64 v[16:17], v[16:17], 0, v[18:19]
	v_lshl_add_u64 v[18:19], s[22:23], 0, v[46:47]
	s_and_b32 s21, s16, 0xfff
	v_add_co_u32_e32 v18, vcc, s8, v18
	s_lshl_b32 s8, s21, 7
	s_add_u32 s8, s6, s8
	s_addc_u32 s9, s7, 0
	s_lshl_b32 s21, s21, 8
	v_addc_co_u32_e32 v19, vcc, 0, v19, vcc
	global_load_dword v133, v214, s[22:23] offset:512
	global_load_dword v117, v[4:5], off offset:3392
	global_load_dword v120, v[4:5], off offset:3456
	global_load_dword v102, v[6:7], off offset:320
	global_load_dword v101, v[16:17], off offset:3648
	global_load_ushort v100, v[18:19], off offset:832
	global_load_dword v103, v[12:13], off offset:64
	v_lshlrev_b32_e32 v12, 3, v25
	s_add_u32 s22, s4, s21
	s_addc_u32 s23, s5, 0
	s_waitcnt lgkmcnt(2)
	v_lshlrev_b32_e32 v26, 3, v8
	global_load_dwordx4 v[16:19], v12, s[8:9]
	global_load_dwordx4 v[4:7], v26, s[22:23]
	s_lshl_b32 s8, s16, 8
	s_and_b32 s21, s8, 0xf00
	s_add_u32 s8, s10, s21
	s_addc_u32 s9, s11, 0
	s_or_b32 s24, s21, 0x1000
	s_add_u32 s22, s10, s24
	s_waitcnt lgkmcnt(0)
; __device__ __forceinline__ void post_store(const PostRegs& R, int m, int lane, bf16_t* __restrict__ P, const f32x4 g4, const f32x2 g2, const float gb, ...
;     bf16_t* pr = P + (size_t)m * NPJ;
;     const int t = m & (SEQ - 1), b = m >> 12;
;     const int i16 = 2 * (lane & 7), i32 = 2 * (lane & 15);
;     const int l0 = t & 15, nc0 = t >> 4, l1 = l0 + 16;
;     const int vg = (2 * lane) >> 6, vd = (2 * lane) & 63;
; __device__ __forceinline__ void post_phase(bf16_t* __restrict__ P, const float* __restrict__ tab32, const float* __restrict__ tab64, ...
;     ...
;     for (int m = gw; m < MROWS; m += NGW) {
;         const int mn = m + NGW;
;         if (mn < MROWS) post_load(Rn, mn, lane, P, tab32, tab64, posK, posV);
;         post_store(Rc, m, lane, P, g4, g2, gb, cqn, ckvn, Kmla, flatK, flatV, gates);
;         Rc = Rn;
	v_lshlrev_b32_e32 v30, 2, v8
	s_addc_u32 s23, s11, 0
	global_load_dwordx2 v[74:75], v30, s[22:23]
	global_load_dwordx2 v[72:73], v30, s[22:23] offset:128
	s_add_u32 s22, s2, s21
	s_addc_u32 s23, s3, 0
	s_add_u32 s24, s2, s24
	v_lshlrev_b32_e32 v28, 2, v22
	s_addc_u32 s25, s3, 0
	global_load_dwordx2 v[78:79], v30, s[8:9]
	global_load_dwordx2 v[76:77], v30, s[8:9] offset:128
	global_load_dwordx2 v[68:69], v28, s[22:23]
	global_load_dwordx2 v[62:63], v28, s[24:25]
	v_mov_b32_e32 v31, v215
	v_mov_b32_e32 v13, v215
	v_lshl_add_u64 v[30:31], s[10:11], 0, v[30:31]
	s_lshl_b32 s10, s26, 9
	v_readlane_b32 s11, v254, 4
	v_lshl_add_u64 v[24:25], s[6:7], 0, v[12:13]
	s_add_i32 s24, s11, s10
	s_mul_hi_i32 s10, s16, 0x300
	v_lshlrev_b32_e32 v13, 2, v9
	v_mov_b32_e32 v27, v215
	v_mov_b32_e32 v29, v215
	v_cmp_gt_u32_e64 s[6:7], s85, v33
	s_mul_i32 s11, s16, 0x300
	v_and_b32_e32 v70, 28, v13
	v_mov_b32_e32 v33, s10
	s_mul_i32 s10, s16, 0x60
	v_lshl_add_u64 v[26:27], s[4:5], 0, v[26:27]
	v_lshl_add_u64 v[28:29], s[2:3], 0, v[28:29]
	v_cmp_lt_u32_e64 s[2:3], 7, v32
	v_cmp_gt_u32_e64 s[4:5], 32, v32
	v_cmp_gt_u32_e64 s[8:9], 24, v32
	v_or_b32_e32 v32, s11, v70
	s_mul_hi_i32 s11, s16, 0x60
	s_add_u32 s10, s10, 0x1c3c1000
	s_addc_u32 s11, s11, 0
	v_lshl_add_u64 v[34:35], s[10:11], 0, v[214:215]
	s_lshl_b64 s[10:11], s[16:17], 8
	s_add_u32 s10, s10, 0x196c1000
	s_addc_u32 s11, s11, 0
	v_or_b32_e32 v36, s10, v214
	v_mov_b32_e32 v37, s11
	s_lshl_b64 s[10:11], s[16:17], 9
	s_add_u32 s10, s10, 0x186c1000
	v_bfe_u32 v99, v9, 4, 2
	s_addc_u32 s11, s11, 0
	v_or_b32_e32 v38, s10, v52
	v_lshlrev_b32_e32 v12, 7, v99
	s_add_u32 s10, s20, 0x96c2140
	v_mov_b32_e32 v39, s11
	v_and_b32_e32 v59, 0x80, v12
	v_and_b32_e32 v66, 60, v13
	s_addc_u32 s11, s19, 0
	v_or3_b32 v42, s10, v59, v66
	s_add_u32 s10, s20, 0x96c1b40
	v_mov_b32_e32 v43, s11
	s_addc_u32 s11, s19, 0
	v_mov_b32_e32 v13, v215
	v_lshl_add_u64 v[44:45], s[10:11], 0, v[12:13]
	v_readlane_b32 s10, v254, 6
	s_add_i32 s10, s10, s18
	s_mul_i32 s18, s10, 0x1400
	s_mul_hi_i32 s17, s10, 0x1400
	s_add_u32 s10, s18, 0x96c2340
	s_addc_u32 s11, s17, 0
	v_or_b32_e32 v46, s10, v46
	s_add_u32 s10, s20, 0x96c1540
	v_mov_b32_e32 v47, s11
	s_addc_u32 s11, s19, 0
	v_lshl_add_u64 v[50:51], s[10:11], 0, v[10:11]
	s_add_u32 s10, s18, 0x96c1000
	s_addc_u32 s11, s17, 0
	v_or_b32_e32 v52, s10, v52
	s_add_u32 s10, s18, 0x96c1200
	v_mov_b32_e32 v53, s11
	s_addc_u32 s11, s17, 0
	v_bfe_u32 v98, v9, 5, 1
	v_or_b32_e32 v54, s10, v214
	s_add_u32 s10, s18, 0x96c1e40
	v_lshlrev_b32_e32 v58, 9, v98
	v_mov_b32_e32 v55, s11
	s_addc_u32 s11, s17, 0
	v_or_b32_e32 v15, s20, v58
	v_or3_b32 v48, s18, v14, v66
	v_lshl_or_b32 v14, v98, 7, s10
	s_add_u32 s10, s18, 0x96c1b40
	v_or3_b32 v40, v15, v59, v66
	v_mov_b32_e32 v15, s11
	s_addc_u32 s11, s17, 0
	v_and_b32_e32 v9, 31, v9
	v_lshl_add_u64 v[64:65], s[10:11], 0, v[12:13]
	s_add_u32 s10, s18, 0x96c1540
	v_lshlrev_b32_e32 v214, 2, v9
	v_or_b32_e32 v9, s18, v58
	s_addc_u32 s11, s17, 0
	v_or_b32_e32 v44, v44, v66
	v_or3_b32 v58, v9, v59, v66
	v_or_b32_e32 v64, v64, v66
	v_lshl_add_u64 v[66:67], s[10:11], 0, v[10:11]
	v_mov_b32_e32 v41, s19
	v_mov_b32_e32 v49, s17
	v_or_b32_e32 v50, v50, v70
	v_lshl_add_u64 v[56:57], v[14:15], 0, v[214:215]
	v_mov_b32_e32 v59, s17
	v_or_b32_e32 v60, s18, v70
	v_mov_b32_e32 v61, s17
	v_or_b32_e32 v66, v66, v70
	v_lshlrev_b32_e32 v214, 1, v8
	s_waitcnt vmcnt(0)
	s_branch .LBB0_937
.LBB0_936:
	s_or_b64 exec, exec, s[10:11]
	s_waitcnt vmcnt(12)
	v_readlane_b32 s10, v253, 62
	v_readlane_b32 s11, v253, 63
	v_mov_b64_e32 v[18:19], v[10:11]
	v_mov_b64_e32 v[4:5], v[12:13]
	v_lshl_add_u64 v[32:33], v[32:33], 0, s[10:11]
	v_readlane_b32 s10, v254, 0
	v_readlane_b32 s11, v254, 1
	s_add_i32 s24, s24, s30
	v_lshl_add_u64 v[36:37], v[36:37], 0, s[34:35]
	v_lshl_add_u64 v[34:35], v[34:35], 0, s[10:11]
	v_readlane_b32 s10, v254, 2
	v_readlane_b32 s11, v254, 3
	v_lshl_add_u64 v[38:39], v[38:39], 0, s[36:37]
	s_and_b64 vcc, exec, s[18:19]
	v_lshl_add_u64 v[40:41], v[40:41], 0, s[10:11]
	v_lshl_add_u64 v[42:43], v[42:43], 0, s[10:11]
	v_lshl_add_u64 v[44:45], v[44:45], 0, s[10:11]
	v_lshl_add_u64 v[46:47], v[46:47], 0, s[10:11]
	v_lshl_add_u64 v[48:49], v[48:49], 0, s[10:11]
	v_lshl_add_u64 v[50:51], v[50:51], 0, s[10:11]
	v_lshl_add_u64 v[52:53], v[52:53], 0, s[10:11]
	v_lshl_add_u64 v[54:55], v[54:55], 0, s[10:11]
	v_lshl_add_u64 v[56:57], v[56:57], 0, s[10:11]
	v_lshl_add_u64 v[58:59], v[58:59], 0, s[10:11]
	v_lshl_add_u64 v[60:61], v[60:61], 0, s[10:11]
	v_lshl_add_u64 v[64:65], v[64:65], 0, s[10:11]
	v_lshl_add_u64 v[66:67], v[66:67], 0, s[10:11]
	s_mov_b32 s16, s25
	v_mov_b64_e32 v[92:93], v[70:71]
	v_mov_b32_e32 v133, v104
	v_mov_b32_e32 v129, v105
	v_mov_b32_e32 v130, v106
	v_mov_b32_e32 v125, v107
	v_mov_b32_e32 v126, v108
	v_mov_b32_e32 v116, v111
	v_mov_b32_e32 v109, v112
	v_mov_b32_e32 v119, v113
	v_mov_b32_e32 v110, v114
	v_mov_b32_e32 v117, v115
	v_mov_b32_e32 v102, v121
	v_mov_b32_e32 v120, v118
	v_mov_b32_e32 v103, v122
	v_mov_b32_e32 v101, v127
	v_mov_b32_e32 v100, v128
	v_mov_b64_e32 v[16:17], v[8:9]
	v_mov_b64_e32 v[6:7], v[14:15]
	s_waitcnt vmcnt(15)
	v_mov_b64_e32 v[78:79], v[80:81]
	s_waitcnt vmcnt(14)
	v_mov_b64_e32 v[76:77], v[82:83]
	v_mov_b64_e32 v[74:75], v[84:85]
	v_mov_b64_e32 v[72:73], v[86:87]
	s_waitcnt vmcnt(13)
	v_mov_b64_e32 v[68:69], v[88:89]
	s_waitcnt vmcnt(12)
	v_mov_b64_e32 v[62:63], v[90:91]
	v_mov_b32_e32 v131, v123
	v_mov_b32_e32 v132, v124
	s_cbranch_vccnz .LBB0_961

; __device__ __forceinline__ unsigned cvtpk(float lo, float hi) { f32x2 v = {lo, hi}; bf16x2_t b = __builtin_convertvector(v, bf16x2_t); return __builtin_bit_cast(unsigned, b); }
; __device__ __forceinline__ float bflo(unsigned u) { return __uint_as_float(u << 16); }
; __device__ __forceinline__ float bfhi(unsigned u) { return __uint_as_float(u & 0xffff0000u); }
; #define ROPE2(a, b2, cs, y1a, y1b, y2a, y2b) \
;     const float y1a = bflo(a) * cs[0] - bflo(b2) * cs[1], y2a = bflo(b2) * cs[0] + bflo(a) * cs[1]; \
;     const float y1b = bfhi(a) * cs[2] - bfhi(b2) * cs[3], y2b = bfhi(b2) * cs[2] + bfhi(a) * cs[3];
; __device__ __forceinline__ void post_store(const PostRegs& R, int m, int lane, bf16_t* __restrict__ P, const f32x4 g4, const f32x2 g2, const float gb, ...
;     ...
;     {
;         const float v0 = bflo(R.r_cq.x), v1 = bfhi(R.r_cq.x), v2 = bflo(R.r_cq.y), v3 = bfhi(R.r_cq.y);
;         const float ss = wave_sum((v0 * v0 + v1 * v1) + (v2 * v2 + v3 * v3));
;         const float rstd = 1.0f / sqrtf(ss * (1.0f / 256) + EPS);
;         u32x2 w; w.x = cvtpk(v0 * rstd * g4[0], v1 * rstd * g4[1]); w.y = cvtpk(v2 * rstd * g4[2], v3 * rstd * g4[3]);
;         *(u32x2*)(cqn + (size_t)m * 256 + 4 * lane) = w;
;     }
;     {
;         const float v0 = bflo(R.r_ckv), v1 = bfhi(R.r_ckv);
;         const float ss = wave_sum(v0 * v0 + v1 * v1);
;         const float rstd = 1.0f / sqrtf(ss * (1.0f / 128) + EPS);
;         *(unsigned*)(ckvn + (size_t)m * 128 + 2 * lane) = cvtpk(v0 * rstd * g2[0], v1 * rstd * g2[1]);
;     }
;     if (lane < 8) {
;         ROPE2(R.r_kr1, R.r_kr2, R.cs32, y1a, y1b, y2a, y2b)
;         const unsigned w1 = cvtpk(y1a, y1b), w2 = cvtpk(y2a, y2b);
; #pragma unroll
;         for (int h = 0; h < 4; ++h) { *(unsigned*)(Kmla + (size_t)m * 384 + h * 96 + 64 + i16) = w1; *(unsigned*)(Kmla + (size_t)m * 384 + h * 96 + 80 + i16) = w2; }
;     }
.LBB0_939:
	v_lshlrev_b32_e32 v94, 16, v93
	v_and_b32_e32 v95, 0xffff0000, v93
	v_lshlrev_b32_e32 v96, 16, v92
	v_and_b32_e32 v97, 0xffff0000, v92
	v_pk_mul_f32 v[134:135], v[94:95], v[94:95]
	v_pk_mul_f32 v[92:93], v[96:97], v[96:97]
	v_add_f32_e32 v134, v134, v135
	v_add_f32_e32 v92, v92, v93
	v_add_f32_e32 v92, v92, v134
	ds_swizzle_b32 v93, v92 offset:swizzle(SWAP,1)
	s_mov_b32 s17, 0xf800000
	s_waitcnt lgkmcnt(0)
	v_add_f32_e32 v93, v92, v93
	ds_swizzle_b32 v134, v93 offset:swizzle(SWAP,2)
	v_lshlrev_b32_e32 v92, 16, v133
	s_waitcnt lgkmcnt(0)
	v_add_f32_e32 v136, v93, v134
	ds_swizzle_b32 v137, v136 offset:swizzle(SWAP,4)
	v_and_b32_e32 v93, 0xffff0000, v133
	v_pk_mul_f32 v[134:135], v[92:93], v[92:93]
	s_nop 0
	v_add_f32_e32 v133, v134, v135
	s_waitcnt lgkmcnt(0)
	v_add_f32_e32 v135, v136, v137
	ds_swizzle_b32 v136, v135 offset:swizzle(SWAP,8)
	ds_swizzle_b32 v134, v133 offset:swizzle(SWAP,1)
	s_waitcnt lgkmcnt(1)
	v_add_f32_e32 v135, v135, v136
	ds_swizzle_b32 v136, v135 offset:swizzle(SWAP,16)
	s_waitcnt lgkmcnt(1)
	v_add_f32_e32 v133, v133, v134
	ds_swizzle_b32 v134, v133 offset:swizzle(SWAP,2)
	s_waitcnt lgkmcnt(1)
	v_add_f32_e32 v135, v135, v136
	v_mov_b32_e32 v136, v135
	s_nop 1
	v_permlane32_swap_b32_e32 v135, v136
	v_add_f32_e32 v135, v135, v136
	v_fmamk_f32 v135, v135, 0x3b800000, v244
	s_waitcnt lgkmcnt(0)
	v_add_f32_e32 v133, v133, v134
	v_mul_f32_e32 v136, 0x4f800000, v135
	v_cmp_gt_f32_e32 vcc, s17, v135
	ds_swizzle_b32 v134, v133 offset:swizzle(SWAP,4)
	s_waitcnt lgkmcnt(0)
	v_add_f32_e32 v133, v133, v134
	v_cndmask_b32_e32 v135, v135, v136, vcc
	v_sqrt_f32_e32 v136, v135
	s_nop 0
	v_add_u32_e32 v134, -1, v136
	v_add_u32_e32 v137, 1, v136
	v_fma_f32 v138, -v134, v136, v135
	v_fma_f32 v139, -v137, v136, v135
	v_cmp_ge_f32_e64 s[10:11], 0, v138
	s_nop 1
	v_cndmask_b32_e64 v134, v136, v134, s[10:11]
	v_cmp_lt_f32_e64 s[10:11], 0, v139
	s_nop 1
	v_cndmask_b32_e64 v134, v134, v137, s[10:11]
	v_mul_f32_e32 v136, 0x37800000, v134
	v_cndmask_b32_e32 v134, v134, v136, vcc
	v_cmp_class_f32_e32 vcc, v135, v245
	ds_swizzle_b32 v137, v133 offset:swizzle(SWAP,8)
	s_waitcnt lgkmcnt(0)
	v_add_f32_e32 v133, v133, v137
	v_cndmask_b32_e32 v134, v134, v135, vcc
	v_div_scale_f32 v135, s[10:11], v134, v134, 1.0
	v_rcp_f32_e32 v136, v135
	v_div_scale_f32 v138, vcc, 1.0, v134, 1.0
	ds_swizzle_b32 v137, v133 offset:swizzle(SWAP,16)
	v_fma_f32 v139, -v135, v136, 1.0
	v_fmac_f32_e32 v136, v139, v136
	v_mul_f32_e32 v139, v138, v136
	v_fma_f32 v140, -v135, v139, v138
	v_fmac_f32_e32 v139, v140, v136
	v_fma_f32 v135, -v135, v139, v138
	v_div_fmas_f32 v135, v135, v136, v139
	v_div_fixup_f32 v134, v135, v134, 1.0
	s_waitcnt lgkmcnt(0)
	v_add_f32_e32 v133, v133, v137
	v_pk_mul_f32 v[96:97], v[134:135], v[96:97] op_sel_hi:[0,1]
	v_mov_b32_e32 v135, v133
	s_nop 1
	v_permlane32_swap_b32_e32 v133, v135
	v_add_f32_e32 v133, v133, v135
	v_fmamk_f32 v133, v133, 0x3c000000, v244
	v_mul_f32_e32 v135, 0x4f800000, v133
	v_cmp_gt_f32_e32 vcc, s17, v133
	v_pk_mul_f32 v[96:97], v[0:1], v[96:97]
	s_nop 0
	v_cndmask_b32_e32 v133, v133, v135, vcc
	v_sqrt_f32_e32 v135, v133
	v_cvt_pk_bf16_f32 v96, v96, v97
	v_add_u32_e32 v97, -1, v135
	v_pk_mul_f32 v[94:95], v[134:135], v[94:95] op_sel_hi:[0,1]
	v_fma_f32 v134, -v97, v135, v133
	v_cmp_ge_f32_e64 s[10:11], 0, v134
	v_add_u32_e32 v134, 1, v135
	v_pk_mul_f32 v[94:95], v[2:3], v[94:95]
	v_cndmask_b32_e64 v97, v135, v97, s[10:11]
	v_fma_f32 v135, -v134, v135, v133
	v_cmp_lt_f32_e64 s[10:11], 0, v135
	s_nop 1
	v_cndmask_b32_e64 v97, v97, v134, s[10:11]
	v_mul_f32_e32 v134, 0x37800000, v97
	v_cndmask_b32_e32 v97, v97, v134, vcc
	v_cmp_class_f32_e32 vcc, v133, v245
	s_nop 1
	v_cndmask_b32_e32 v133, v97, v133, vcc
	v_div_scale_f32 v134, s[10:11], v133, v133, 1.0
	v_rcp_f32_e32 v135, v134
	v_readlane_b32 s10, v254, 50
	v_readlane_b32 s11, v254, 51
	v_cvt_pk_bf16_f32 v97, v94, v95
	s_nop 0
	v_lshl_add_u64 v[94:95], s[10:11], 0, v[38:39]
	global_store_dwordx2 v[94:95], v[96:97], off
	v_fma_f32 v94, -v134, v135, 1.0
	v_fmac_f32_e32 v135, v94, v135
	v_div_scale_f32 v94, vcc, 1.0, v133, 1.0
	v_mul_f32_e32 v95, v94, v135
	v_fma_f32 v96, -v134, v95, v94
	v_fmac_f32_e32 v95, v96, v135
	v_fma_f32 v94, -v134, v95, v94
	v_div_fmas_f32 v94, v94, v135, v95
	v_div_fixup_f32 v94, v94, v133, 1.0
	v_pk_mul_f32 v[92:93], v[94:95], v[92:93] op_sel_hi:[0,1]
	v_pk_mul_f32 v[92:93], v[20:21], v[92:93]
	s_nop 0
	v_cvt_pk_bf16_f32 v94, v92, v93
	v_lshl_add_u64 v[92:93], s[10:11], 0, v[36:37]
	global_store_dword v[92:93], v94, off
	s_and_saveexec_b64 s[10:11], s[2:3]
	s_xor_b64 s[10:11], exec, s[10:11]
	s_cbranch_execz .LBB0_941
	v_mov_b32_e32 v93, v19
	v_mov_b32_e32 v92, v17
	v_mov_b32_e32 v17, v18
.LBB0_941:
	s_andn2_saveexec_b64 s[10:11], s[10:11]
	s_cbranch_execz .LBB0_943
	v_and_b32_e32 v95, 0xffff0000, v132
	v_lshlrev_b32_e32 v97, 16, v132
	v_and_b32_e32 v93, 16, v132
	v_and_b32_e32 v92, 0xffff0000, v131
	v_pk_mov_b32 v[132:133], v[96:97], v[92:93] op_sel:[1,0]
	v_mov_b32_e32 v137, v92
	v_mov_b32_e32 v92, v17
	v_mov_b32_e32 v93, v19
	v_mov_b32_e32 v96, v97
	v_mov_b32_e32 v97, v95
	v_mov_b32_e32 v17, v19
	v_lshlrev_b32_e32 v94, 16, v131
	v_pk_mul_f32 v[96:97], v[92:93], v[96:97]
	v_mov_b32_e32 v93, v18
	v_pk_mul_f32 v[132:133], v[16:17], v[132:133]
	v_readlane_b32 s20, v254, 50
	v_mov_b32_e32 v136, v94
	v_pk_fma_f32 v[94:95], v[92:93], v[94:95], v[132:133]
	v_readlane_b32 s21, v254, 51
	v_mov_b32_e32 v134, v16
	v_mov_b32_e32 v135, v18
	v_cvt_pk_bf16_f32 v93, v94, v95
	v_lshl_add_u64 v[94:95], s[20:21], 0, v[32:33]
	v_pk_fma_f32 v[96:97], v[134:135], v[136:137], v[96:97] neg_lo:[0,0,1] neg_hi:[0,0,1]
	v_add_co_u32_e32 v94, vcc, 0x15ec1000, v94
	v_cvt_pk_bf16_f32 v17, v96, v97
	s_nop 0
	v_addc_co_u32_e32 v95, vcc, 0, v95, vcc
	global_store_dword v[94:95], v17, off offset:128
	global_store_dword v[94:95], v93, off offset:160
	global_store_dword v[94:95], v17, off offset:320
	global_store_dword v[94:95], v93, off offset:352
	global_store_dword v[94:95], v17, off offset:512
	global_store_dword v[94:95], v93, off offset:544
	global_store_dword v[94:95], v17, off offset:704
	global_store_dword v[94:95], v93, off offset:736
	v_mov_b32_e32 v17, v18
	v_mov_b32_e32 v93, v19
; __device__ __forceinline__ unsigned cvtpk(float lo, float hi) { f32x2 v = {lo, hi}; bf16x2_t b = __builtin_convertvector(v, bf16x2_t); return __builtin_bit_cast(unsigned, b); }
; #define ROPE2(a, b2, cs, y1a, y1b, y2a, y2b) \
;     const float y1a = bflo(a) * cs[0] - bflo(b2) * cs[1], y2a = bflo(b2) * cs[0] + bflo(a) * cs[1]; \
;     const float y1b = bfhi(a) * cs[2] - bfhi(b2) * cs[3], y2b = bfhi(b2) * cs[2] + bfhi(a) * cs[3];
; __device__ __forceinline__ void post_store(const PostRegs& R, int m, int lane, bf16_t* __restrict__ P, const f32x4 g4, const f32x2 g2, const float gb, ...
;     ...
;     {
;         const int ch = lane >> 3;
;         { ROPE2(R.dq1, R.dq2, R.cs32, y1a, y1b, y2a, y2b)
;           bf16_t* q = pr + C_DQ + ch * 32 + i16; *(unsigned*)q = cvtpk(y1a * QS_DIFF, y1b * QS_DIFF); *(unsigned*)(q + 16) = cvtpk(y2a * QS_DIFF, y2b * QS_DIFF); }
;         { ROPE2(R.dk1, R.dk2, R.cs32, y1a, y1b, y2a, y2b)
;           bf16_t* k = pr + C_DK + ch * 32 + i16; *(unsigned*)k = cvtpk(y1a, y1b); *(unsigned*)(k + 16) = cvtpk(y2a, y2b); }
;     }
; #pragma unroll
;     for (int rep = 0; rep < 2; ++rep) {
;         const int ch = (lane + 64 * rep) >> 4;
;         ROPE2(R.nq1[rep], R.nq2[rep], R.cs64, y1a, y1b, y2a, y2b)
;         bf16_t* q = pr + C_NQ + ch * 64 + i32; *(unsigned*)q = cvtpk(y1a * QS_NSA, y1b * QS_NSA); *(unsigned*)(q + 32) = cvtpk(y2a * QS_NSA, y2b * QS_NSA);
;     }
; #pragma unroll
;     for (int rep = 0; rep < 2; ++rep) {
;         const int ch = (lane + 64 * rep) >> 4;
;         if (ch < 6) {
;             const int br = ch >> 1, g = ch & 1;
;             ROPE2(R.nk1[rep], R.nk2[rep], R.cs64, y1a, y1b, y2a, y2b)
;             bf16_t* k = pr + C_NKV + br * 256 + g * 64 + i32; *(unsigned*)k = cvtpk(y1a, y1b); *(unsigned*)(k + 32) = cvtpk(y2a, y2b);
;             if (br == 0) {
;                 const size_t rowb = (size_t)(b * 2 + g) * 256;
;                 if (nc0 <= 254) { bf16_t* f = flatK + (rowb + nc0) * 2048 + l0 * 64 + i32; *(unsigned*)f = cvtpk(y1a + R.pk0a[0], y1b + R.pk0a[1]); *(unsigned*)(f + 32) = cvtpk(y2a + R.pk0b[0], y2b + R.pk0b[1]); }
;                 if (nc0 >= 1) { bf16_t* f = flatK + (rowb + nc0 - 1) * 2048 + l1 * 64 + i32; *(unsigned*)f = cvtpk(y1a + R.pk1a[0], y1b + R.pk1a[1]); *(unsigned*)(f + 32) = cvtpk(y2a + R.pk1b[0], y2b + R.pk1b[1]); }
;             }
;         }
.LBB0_943:
	s_or_b64 exec, exec, s[10:11]
	v_lshlrev_b32_e32 v94, 16, v130
	v_and_b32_e32 v95, 0xffff0000, v130
	v_lshlrev_b32_e32 v18, 16, v129
	v_and_b32_e32 v19, 0xffff0000, v129
	v_pk_mul_f32 v[130:131], v[92:93], v[94:95]
	v_pk_mul_f32 v[94:95], v[16:17], v[94:95]
	v_readlane_b32 s22, v254, 50
	v_pk_fma_f32 v[130:131], v[16:17], v[18:19], v[130:131] neg_lo:[0,0,1] neg_hi:[0,0,1]
	v_pk_fma_f32 v[18:19], v[92:93], v[18:19], v[94:95]
	v_readlane_b32 s23, v254, 51
	v_pk_mul_f32 v[18:19], v[18:19], s[38:39] op_sel_hi:[1,0]
	v_pk_mul_f32 v[130:131], v[130:131], s[38:39] op_sel_hi:[1,0]
	v_lshl_add_u64 v[96:97], s[22:23], 0, v[50:51]
	v_cvt_pk_bf16_f32 v18, v18, v19
	v_lshlrev_b32_e32 v94, 16, v126
	v_and_b32_e32 v95, 0xffff0000, v126
	v_cvt_pk_bf16_f32 v129, v130, v131
	global_store_dword v[96:97], v18, off offset:-480
	v_lshlrev_b32_e32 v18, 16, v125
	v_and_b32_e32 v19, 0xffff0000, v125
	v_pk_mul_f32 v[130:131], v[92:93], v[94:95]
	global_store_dword v[96:97], v129, off offset:-512
	v_pk_fma_f32 v[130:131], v[16:17], v[18:19], v[130:131] neg_lo:[0,0,1] neg_hi:[0,0,1]
	v_pk_mul_f32 v[16:17], v[16:17], v[94:95]
	v_lshl_add_u64 v[94:95], s[22:23], 0, v[44:45]
	v_pk_fma_f32 v[16:17], v[92:93], v[18:19], v[16:17]
	v_cvt_pk_bf16_f32 v18, v130, v131
	v_cvt_pk_bf16_f32 v16, v16, v17
	v_lshlrev_b32_e32 v92, 16, v119
	v_and_b32_e32 v93, 0xffff0000, v119
	v_mov_b32_e32 v17, v6
	v_mov_b32_e32 v6, v5
	global_store_dword v[96:97], v18, off
	global_store_dword v[96:97], v16, off offset:32
	v_lshlrev_b32_e32 v18, 16, v116
	v_and_b32_e32 v19, 0xffff0000, v116
	v_mov_b32_e32 v16, v4
	v_pk_mul_f32 v[4:5], v[6:7], v[92:93]
	s_ashr_i32 s11, s16, 11
	v_pk_fma_f32 v[4:5], v[16:17], v[18:19], v[4:5] neg_lo:[0,0,1] neg_hi:[0,0,1]
	s_bfe_u32 s10, s16, 0x80004
	v_pk_mul_f32 v[4:5], v[4:5], s[40:41] op_sel_hi:[1,0]
	s_and_b32 s27, s11, -2
	v_cvt_pk_bf16_f32 v4, v4, v5
	global_store_dword v[94:95], v4, off offset:-512
	v_pk_mul_f32 v[4:5], v[6:7], v[18:19]
	v_lshlrev_b32_e32 v18, 16, v110
	v_pk_fma_f32 v[4:5], v[16:17], v[92:93], v[4:5]
	v_and_b32_e32 v19, 0xffff0000, v110
	v_pk_mul_f32 v[4:5], v[4:5], s[40:41] op_sel_hi:[1,0]
	v_pk_mul_f32 v[92:93], v[6:7], v[18:19]
	v_cvt_pk_bf16_f32 v4, v4, v5
	global_store_dword v[94:95], v4, off offset:-448
	v_lshlrev_b32_e32 v4, 16, v109
	v_and_b32_e32 v5, 0xffff0000, v109
	v_pk_fma_f32 v[92:93], v[16:17], v[4:5], v[92:93] neg_lo:[0,0,1] neg_hi:[0,0,1]
	v_pk_mul_f32 v[4:5], v[6:7], v[4:5]
	v_pk_mul_f32 v[92:93], v[92:93], s[40:41] op_sel_hi:[1,0]
	v_pk_fma_f32 v[4:5], v[16:17], v[18:19], v[4:5]
	v_cvt_pk_bf16_f32 v92, v92, v93
	v_pk_mul_f32 v[4:5], v[4:5], s[40:41] op_sel_hi:[1,0]
	global_store_dword v[94:95], v92, off
	v_cvt_pk_bf16_f32 v4, v4, v5
	v_lshlrev_b32_e32 v92, 16, v120
	v_and_b32_e32 v93, 0xffff0000, v120
	global_store_dword v[94:95], v4, off offset:64
	v_lshlrev_b32_e32 v4, 16, v117
	v_and_b32_e32 v5, 0xffff0000, v117
	v_pk_mul_f32 v[18:19], v[6:7], v[92:93]
	s_cmpk_eq_i32 s10, 0xff
	v_pk_fma_f32 v[18:19], v[16:17], v[4:5], v[18:19] neg_lo:[0,0,1] neg_hi:[0,0,1]
	v_pk_mul_f32 v[4:5], v[6:7], v[4:5]
	s_cselect_b64 s[20:21], -1, 0
	s_cmpk_lg_i32 s10, 0xff
	v_pk_fma_f32 v[4:5], v[16:17], v[92:93], v[4:5]
	v_lshl_add_u64 v[92:93], s[22:23], 0, v[40:41]
	s_cselect_b64 s[16:17], -1, 0
	s_lshl_b32 s80, s10, 12
	s_and_b32 s26, s24, 0x3c0
	v_add_co_u32_e32 v92, vcc, 0x96c1000, v92
	s_cmp_lg_u32 s10, 0
	v_cvt_pk_bf16_f32 v94, v18, v19
	v_addc_co_u32_e32 v93, vcc, 0, v93, vcc
	s_cselect_b64 s[10:11], -1, 0
	global_store_dword v[92:93], v94, off offset:3392
	v_cvt_pk_bf16_f32 v94, v4, v5
	global_store_dword v[92:93], v94, off offset:3456
	s_and_saveexec_b64 s[22:23], s[4:5]
	s_cbranch_execz .LBB0_948
	v_add_u32_e32 v92, s27, v99
	v_ashrrev_i32_e32 v93, 31, v92
	v_lshlrev_b64 v[92:93], 20, v[92:93]
	v_lshl_add_u64 v[92:93], s[12:13], 0, v[92:93]
	v_lshl_add_u64 v[92:93], v[92:93], 0, s[80:81]
	s_lshl_b32 s28, s26, 1
	s_mov_b32 s29, s81
	v_lshl_add_u64 v[92:93], v[92:93], 0, s[28:29]
	s_andn2_b64 vcc, exec, s[16:17]
	v_lshl_add_u64 v[92:93], v[92:93], 0, v[214:215]
	s_cbranch_vccnz .LBB0_946
	v_pk_add_f32 v[78:79], v[78:79], v[18:19]
	v_pk_add_f32 v[76:77], v[76:77], v[4:5]
	v_cvt_pk_bf16_f32 v78, v78, v79
	v_cvt_pk_bf16_f32 v76, v76, v77
	s_mov_b64 s[20:21], s[10:11]
	global_store_dword v[92:93], v78, off
	global_store_dword v[92:93], v76, off offset:64
.LBB0_946:
	s_andn2_b64 vcc, exec, s[20:21]
	s_cbranch_vccnz .LBB0_948
	v_pk_add_f32 v[18:19], v[18:19], v[74:75]
	v_pk_add_f32 v[4:5], v[4:5], v[72:73]
	v_cvt_pk_bf16_f32 v18, v18, v19
	v_cvt_pk_bf16_f32 v4, v4, v5
	global_store_dword v[92:93], v18, off offset:-2048
	global_store_dword v[92:93], v4, off offset:-1984
.LBB0_948:
	s_or_b64 exec, exec, s[22:23]
	s_and_saveexec_b64 s[20:21], s[6:7]
	s_cbranch_execz .LBB0_950
	v_lshlrev_b32_e32 v18, 16, v103
	v_and_b32_e32 v19, 0xffff0000, v103
	v_lshlrev_b32_e32 v4, 16, v102
	v_and_b32_e32 v5, 0xffff0000, v102
	v_pk_mul_f32 v[72:73], v[6:7], v[18:19]
	v_readlane_b32 s22, v254, 50
	v_pk_fma_f32 v[72:73], v[16:17], v[4:5], v[72:73] neg_lo:[0,0,1] neg_hi:[0,0,1]
	v_pk_mul_f32 v[4:5], v[6:7], v[4:5]
	v_readlane_b32 s23, v254, 51
	v_pk_fma_f32 v[4:5], v[16:17], v[18:19], v[4:5]
	v_cvt_pk_bf16_f32 v16, v72, v73
	v_lshl_add_u64 v[6:7], s[22:23], 0, v[42:43]
	v_cvt_pk_bf16_f32 v4, v4, v5
	global_store_dword v[6:7], v16, off
	global_store_dword v[6:7], v4, off offset:64
.LBB0_950:
	s_or_b64 exec, exec, s[20:21]
	v_or_b32_e32 v6, s27, v98
	v_ashrrev_i32_e32 v7, 31, v6
	v_lshlrev_b32_e32 v4, 16, v101
	v_and_b32_e32 v5, 0xffff0000, v101
	s_and_b64 vcc, exec, s[16:17]
	v_lshlrev_b64 v[16:17], 20, v[6:7]
	v_lshlrev_b32_e32 v6, 1, v22
	s_cbranch_vccz .LBB0_952
	v_pk_add_f32 v[18:19], v[68:69], v[4:5]
	v_mov_b32_e32 v7, v215
	v_cvt_pk_bf16_f32 v72, v18, v19
	v_or_b32_e32 v18, s80, v16
	v_mov_b32_e32 v19, v17
	v_lshl_add_u64 v[68:69], s[14:15], 0, v[18:19]
	s_lshl_b32 s80, s26, 1
	v_lshl_add_u64 v[68:69], v[68:69], 0, s[80:81]
	v_lshl_add_u64 v[68:69], v[68:69], 0, v[6:7]
	global_store_dword v[68:69], v72, off
	s_cbranch_execz .LBB0_953
	s_branch .LBB0_954

; __device__ __forceinline__ float bf2f(bf16_t h) { return __uint_as_float((unsigned)h << 16); }
; __device__ __forceinline__ unsigned cvtpk(float lo, float hi) { f32x2 v = {lo, hi}; bf16x2_t b = __builtin_convertvector(v, bf16x2_t); return __builtin_bit_cast(unsigned, b); }
; __device__ __forceinline__ float bflo(unsigned u) { return __uint_as_float(u << 16); }
; __device__ __forceinline__ float bfhi(unsigned u) { return __uint_as_float(u & 0xffff0000u); }
; __device__ __forceinline__ void post_store(const PostRegs& R, int m, int lane, bf16_t* __restrict__ P, const f32x4 g4, const f32x2 g2, const float gb, ...
;     ...
;     {
;         const float v0 = bflo(R.r_v), v1 = bfhi(R.r_v);
;         const size_t rowb = (size_t)(b * 2 + vg) * 256;
;         if (nc0 <= 254) *(unsigned*)(flatV + (rowb + nc0) * 2048 + l0 * 64 + vd) = cvtpk(v0 + R.pv0[0], v1 + R.pv0[1]);
;         if (nc0 >= 1) *(unsigned*)(flatV + (rowb + nc0 - 1) * 2048 + l1 * 64 + vd) = cvtpk(v0 + R.pv1[0], v1 + R.pv1[1]);
;     }
;     if (lane < 24) { const float z = bf2f(R.r_gate) + gb; gates[(size_t)m * 24 + lane] = 1.0f / (1.0f + __expf(-z)); }
.LBB0_956:
	v_pk_add_f32 v[4:5], v[62:63], v[4:5]
	s_lshl_b32 s80, s26, 1
	v_cvt_pk_bf16_f32 v16, v4, v5
	v_lshl_add_u64 v[4:5], s[14:15], 0, v[18:19]
	v_lshl_add_u64 v[4:5], v[4:5], 0, s[80:81]
	v_mov_b32_e32 v7, v215
	v_lshl_add_u64 v[4:5], v[4:5], 0, v[6:7]
	global_store_dword v[4:5], v16, off offset:-2048
	s_and_saveexec_b64 s[10:11], s[8:9]
	s_cbranch_execz .LBB0_936
